# seam 0: flat arrival-counter barrier (release/acquire at agent scope, bounded spin) instead of cg grid.sync; on top of the register-resident GLA recurrence
# speedup vs baseline: 1.0270x; 1.0078x over previous
; #define SEAM(k) do { if (IN(k) && IN((k) + 1)) { if ((k) == 0) grid.sync(); else xcd_barrier(xbar); } } while (0)
; __global__ void __launch_bounds__(512, 2) hybrid_fwd(Args a) {
;     ...
;     if (IN(0)) { phase0(a, lds, tid); } SEAM(0);
.LBB0_139:
	s_cmp_gt_i32 s91, 1
	s_cselect_b64 s[0:1], -1, 0
	s_and_b64 s[4:5], s[14:15], s[0:1]
	s_andn2_b64 vcc, exec, s[4:5]
	s_cbranch_vccnz .LBB0_151
	s_waitcnt vmcnt(0) lgkmcnt(0)
	s_barrier
	v_cmp_eq_u32_e32 vcc, 0, v188
	s_and_saveexec_b64 s[4:5], vcc
	s_cbranch_execz .Lfb_done
	buffer_wbl2 sc1
	s_waitcnt vmcnt(0)
	v_mov_b32_e32 v0, 0
	v_mov_b32_e32 v1, 1
	s_add_u32 s6, s86, 0x236b0
	s_addc_u32 s7, s87, 0
	global_atomic_add v0, v1, s[6:7]
	v_readlane_b32 s3, v249, 21
	s_mov_b32 s12, 0x40000
.Lfb_spin:
	global_load_dword v2, v0, s[6:7] sc1
	s_waitcnt vmcnt(0)
	v_readfirstlane_b32 s13, v2
	s_cmp_ge_u32 s13, s3
	s_cbranch_scc1 .Lfb_rel
	s_sleep 1
	s_sub_u32 s12, s12, 1
	s_cmp_lg_u32 s12, 0
	s_cbranch_scc1 .Lfb_spin
.Lfb_rel:
	buffer_inv sc1
	s_waitcnt vmcnt(0)
